# stack7 + weight (B operand) touch-prefetch into L2/MALL at the start of every GEMM phase (P1,P3,P4,P6,P8)
# baseline (speedup 1.0000x reference)
.Lp1_skipdefer:
	s_cmpk_lt_i32 s2, 0x400
	v_mov_b32_e32 v8, v210
	v_writelane_b32 v232, s24, 47
	s_waitcnt lgkmcnt(0)
	s_barrier
	s_cselect_b64 s[0:1], -1, 0
	v_lshl_add_u32 v236, s2, 9, v210
	v_mov_b32_e32 v237, 0
	v_lshlrev_b64 v[236:237], 7, v[236:237]
	s_add_u32 s98, s92, 0x400000
	s_addc_u32 s99, s93, 0
	v_lshl_add_u64 v[236:237], s[98:99], 0, v[236:237]
	global_load_dword v234, v[236:237], off
	s_cmpk_gt_i32 s2, 0x3ff
	v_writelane_b32 v232, s25, 48
	v_readfirstlane_b32 s4, v8
	s_cbranch_scc1 .LBB0_130
	s_ashr_i32 s3, s2, 31
	s_lshr_b32 s3, s3, 29
	s_add_i32 s3, s2, s3
	s_and_b32 s5, s3, -8
	s_sub_i32 s5, s2, s5
	s_lshl_b32 s13, s5, 7
	s_ashr_i32 s3, s3, 3
	s_mul_i32 s12, s5, 0x81
	s_cmp_lt_i32 s5, 0
	s_cselect_b32 s5, s12, s13
	s_add_i32 s3, s5, s3
	s_ashr_i32 s5, s3, 31
	s_lshr_b32 s5, s5, 26
	s_add_i32 s5, s3, s5
	s_ashr_i32 s12, s5, 6
	s_andn2_b32 s5, s5, 63
	s_sub_i32 s3, s3, s5
	s_bfe_i32 s5, s3, 0x80000
	s_bfe_u32 s5, s5, 0x2000d
	s_add_i32 s5, s3, s5
	s_bfe_i32 s13, s5, 0x80000
	s_and_b32 s5, s5, 0xfc
	s_sub_i32 s3, s3, s5
	s_lshl_b32 s12, s12, 2
	s_sext_i32_i16 s13, s13
	s_sext_i32_i8 s3, s3
	s_add_i32 s14, s12, s3
	s_ashr_i32 s12, s13, 2

.LBB0_386:
	s_or_b64 exec, exec, s[0:1]
	s_add_u32 s20, s92, 0x11d00000
	s_addc_u32 s21, s93, 0
	s_add_u32 s18, s92, 0x17d00000
	s_addc_u32 s19, s93, 0
	v_mov_b32_e32 v16, v210
	s_waitcnt lgkmcnt(0)
	s_barrier
	v_lshl_add_u32 v236, s2, 9, v210
	v_mov_b32_e32 v237, 0
	v_lshlrev_b64 v[236:237], 7, v[236:237]
	s_add_u32 s98, s92, 0x3000000
	s_addc_u32 s99, s93, 0
	v_lshl_add_u64 v[236:237], s[98:99], 0, v[236:237]
	global_load_dword v234, v[236:237], off
	s_cmpk_gt_i32 s2, 0x17f
	v_writelane_b32 v232, s78, 52
	v_readfirstlane_b32 s14, v16
	s_nop 0
	v_writelane_b32 v232, s79, 53
	s_cbranch_scc1 .LBB0_406
	v_lshlrev_b32_e32 v0, 4, v16
	v_add_u32_e32 v1, 0x2000, v0
	v_ashrrev_i32_e32 v2, 31, v1
	v_lshrrev_b32_e32 v2, 22, v2
	v_add_u32_e32 v2, v1, v2
	v_ashrrev_i32_e32 v8, 10, v2
	v_mul_i32_i24_e32 v2, 0x400, v8
	v_sub_u32_e32 v1, v1, v2
	v_lshrrev_b32_e32 v2, 4, v1
	v_bitop3_b32 v1, v2, v1, 32 bitop3:0x6c
	v_ashrrev_i32_e32 v2, 31, v1
	v_lshrrev_b32_e32 v2, 26, v2
	v_add_u32_e32 v2, v1, v2
	v_lshlrev_b32_e32 v3, 3, v8
	v_ashrrev_i32_e32 v9, 6, v2
	v_and_b32_e32 v3, -16, v3
	v_add_u32_e32 v3, v9, v3
	v_and_b32_e32 v4, 3, v9
	s_mov_b32 s0, 0x7fffe0
	v_lshrrev_b32_e32 v5, 2, v3
	v_lshlrev_b32_e32 v6, 1, v3
	v_and_b32_e32 v2, 0xc0, v2
	v_and_or_b32 v4, v3, s0, v4
	v_and_b32_e32 v5, 4, v5
	v_and_b32_e32 v6, 24, v6
	v_sub_u32_e32 v1, v1, v2
	v_mov_b32_e32 v2, 1
	v_or3_b32 v4, v4, v5, v6
	v_lshlrev_b32_e32 v5, 5, v8
	v_ashrrev_i16_sdwa v1, v2, sext(v1) dst_sel:DWORD dst_unused:UNUSED_PAD src0_sel:DWORD src1_sel:BYTE_0
	s_movk_i32 s15, 0x600
	v_and_b32_e32 v10, 32, v5
	v_bfe_i32 v11, v1, 0, 16
	v_mul_u32_u24_e32 v4, 0x600, v4
	v_add_u32_e32 v1, v10, v11
	v_mul_lo_u32 v3, v3, s15
	v_add_lshl_u32 v168, v4, v1, 1
	v_add_lshl_u32 v170, v1, v3, 1
	v_bfe_i32 v1, v16, 27, 1
	v_lshrrev_b32_e32 v1, 22, v1
	v_add_u32_e32 v1, v0, v1
	v_and_b32_e32 v1, 0xfffffc00, v1
	v_sub_u32_e32 v0, v0, v1
	v_lshrrev_b32_e32 v1, 4, v0
	v_bitop3_b32 v1, v1, v0, 32 bitop3:0x6c
	v_ashrrev_i32_e32 v0, 31, v0
	v_lshrrev_b32_e32 v0, 26, v0
	v_add_u32_e32 v0, v1, v0
	v_ashrrev_i32_e32 v12, 6, v0
	v_ashrrev_i32_e32 v0, 31, v16
	v_lshrrev_b32_e32 v0, 26, v0
	v_add_u32_e32 v0, v16, v0
	v_ashrrev_i32_e32 v13, 6, v0
	v_lshlrev_b32_e32 v0, 3, v13
	v_and_b32_e32 v0, -16, v0
	s_add_u32 s33, s92, 0x3000000
	v_add_u32_e32 v0, v12, v0
	v_and_b32_e32 v3, 3, v12
	s_addc_u32 s48, s93, 0
	v_and_or_b32 v3, v0, s0, v3
	s_lshr_b32 s0, s3, 29
	s_add_i32 s0, s2, s0
	s_ashr_i32 s22, s14, 6
	s_ashr_i32 s1, s0, 3
	s_and_b32 s0, s0, -8
	s_ashr_i32 s23, s14, 8
	s_lshl_b32 s49, s22, 10
	s_sub_i32 s0, s2, s0
	s_cmp_lt_i32 s0, 0
	s_cselect_b32 s4, 49, 48
	s_mul_i32 s0, s0, s4
	s_add_i32 s0, s0, s1
	s_mul_hi_i32 s1, s0, 0x2aaaaaab
	s_lshr_b32 s4, s1, 31
	s_ashr_i32 s1, s1, 2
	s_add_i32 s1, s1, s4
	s_lshl_b32 s4, s1, 2
	s_mul_i32 s1, s1, 24
	s_sub_i32 s0, s0, s1
	s_bfe_i32 s1, s0, 0x80000
	s_bfe_u32 s1, s1, 0x2000d
	v_lshrrev_b32_e32 v4, 2, v0
	v_lshlrev_b32_e32 v5, 1, v0
	s_add_i32 s1, s0, s1
	v_and_b32_e32 v4, 4, v4
	v_and_b32_e32 v5, 24, v5
	s_bfe_i32 s5, s1, 0x80000
	s_and_b32 s1, s1, 0xfc
	v_or3_b32 v3, v3, v4, v5
	v_lshlrev_b32_e32 v4, 5, v13
	s_sub_i32 s0, s0, s1
	v_and_b32_e32 v14, 32, v4
	v_mul_i32_i24_e32 v4, 64, v12
	s_sext_i32_i16 s5, s5
	s_sext_i32_i8 s0, s0
	v_sub_u32_e32 v1, v1, v4
	s_add_i32 s76, s4, s0
	s_ashr_i32 s0, s5, 2
	v_ashrrev_i16_sdwa v1, v2, sext(v1) dst_sel:DWORD dst_unused:UNUSED_PAD src0_sel:DWORD src1_sel:BYTE_0
	s_lshr_b32 s25, s5, 2
	s_mul_hi_i32 s1, s0, 0xc0000
	s_mul_i32 s0, s0, 0xc0000
	v_bfe_i32 v15, v1, 0, 16
	s_add_u32 s12, s33, s0
	v_mul_u32_u24_e32 v3, 0x600, v3
	v_add_u32_e32 v1, v14, v15
	s_addc_u32 s13, s48, s1
	s_add_i32 s50, s49, 0
	v_add_lshl_u32 v172, v3, v1, 1
	s_add_i32 m0, s50, 0x10000
	s_mul_i32 s4, s76, 0xc0000
	global_load_lds_dwordx4 v172, s[12:13]
	s_add_i32 m0, s50, 0x12000
	s_add_u32 s0, s12, 0x60000
	global_load_lds_dwordx4 v168, s[12:13]
	s_addc_u32 s1, s13, 0
	s_add_i32 m0, s50, 0x14000
	s_mul_hi_i32 s24, s76, 0xc0000
	global_load_lds_dwordx4 v172, s[0:1]
	s_add_i32 m0, s50, 0x16000
	s_add_u32 s4, s20, s4
	v_mul_lo_u32 v0, v0, s15
	s_addc_u32 s5, s21, s24
	s_add_i32 s51, s50, 0x2000
	v_add_lshl_u32 v174, v1, v0, 1
	global_load_lds_dwordx4 v168, s[0:1]
	s_mov_b32 m0, s50
	s_add_u32 s0, s4, 0x60000
	global_load_lds_dwordx4 v174, s[4:5]
	s_mov_b32 m0, s51
	s_addc_u32 s1, s5, 0
	s_add_i32 s52, s50, 0x4000
	global_load_lds_dwordx4 v170, s[4:5]
	s_mov_b32 m0, s52
	s_add_i32 s53, s50, 0x6000
	global_load_lds_dwordx4 v174, s[0:1]
	s_mov_b32 m0, s53
	v_mov_b32_e32 v173, 0
	global_load_lds_dwordx4 v170, s[0:1]
	v_mov_b32_e32 v169, v173
	v_mov_b32_e32 v175, v173
	v_mov_b32_e32 v171, v173
	s_cmp_eq_u32 s23, 1
	s_mov_b32 s62, 0
	v_lshl_add_u64 v[6:7], s[12:13], 0, v[172:173]
	v_lshl_add_u64 v[4:5], s[12:13], 0, v[168:169]
	v_lshl_add_u64 v[2:3], s[4:5], 0, v[174:175]
	v_lshl_add_u64 v[0:1], s[4:5], 0, v[170:171]
	s_cselect_b64 s[0:1], -1, 0
	s_cmp_lg_u32 s23, 1
	s_movk_i32 s24, 0x6000
	s_cbranch_scc1 .LBB0_389
	s_barrier

.LBB0_627:
	s_or_b64 exec, exec, s[0:1]
	s_cmpk_lt_i32 s2, 0x200
	v_mov_b32_e32 v11, v210
	s_waitcnt lgkmcnt(0)
	s_barrier
	s_cselect_b64 s[0:1], -1, 0
	v_lshl_add_u32 v236, s2, 9, v210
	v_mov_b32_e32 v237, 0
	v_lshlrev_b64 v[236:237], 7, v[236:237]
	s_add_u32 s98, s92, 0x3d00000
	s_addc_u32 s99, s93, 0
	v_lshl_add_u64 v[236:237], s[98:99], 0, v[236:237]
	global_load_dword v234, v[236:237], off
	s_cmpk_gt_i32 s2, 0x1ff
	s_nop 0
	v_readfirstlane_b32 s24, v11
	s_cbranch_scc1 .LBB0_629
	s_lshr_b32 s4, s3, 29
	s_add_i32 s4, s2, s4
	s_and_b32 s5, s4, -8
	s_sub_i32 s5, s2, s5
	s_lshl_b32 s13, s5, 6
	s_ashr_i32 s4, s4, 3
	s_mul_i32 s12, s5, 0x41
	s_cmp_lt_i32 s5, 0
	s_cselect_b32 s5, s12, s13
	s_add_i32 s4, s5, s4
	s_ashr_i32 s5, s4, 31
	s_lshr_b32 s5, s5, 27
	s_add_i32 s5, s4, s5
	s_ashr_i32 s12, s5, 5
	s_andn2_b32 s5, s5, 31
	s_sub_i32 s4, s4, s5
	s_bfe_i32 s5, s4, 0x80000
	s_bfe_u32 s5, s5, 0x2000d
	s_add_i32 s5, s4, s5
	s_bfe_i32 s13, s5, 0x80000
	s_and_b32 s5, s5, 0xfc
	s_sub_i32 s4, s4, s5
	s_lshl_b32 s12, s12, 2
	s_sext_i32_i16 s13, s13
	s_sext_i32_i8 s4, s4
	s_add_i32 s56, s12, s4
	s_ashr_i32 s14, s13, 2

.LBB0_1224:
	s_or_b64 exec, exec, s[0:1]
	v_mov_b32_e32 v12, v210
	s_waitcnt lgkmcnt(0)
	s_barrier
	v_lshl_add_u32 v236, s2, 9, v210
	v_mov_b32_e32 v237, 0
	v_lshlrev_b64 v[236:237], 7, v[236:237]
	s_add_u32 s98, s92, 0x4500000
	s_addc_u32 s99, s93, 0
	v_lshl_add_u64 v[236:237], s[98:99], 0, v[236:237]
	global_load_dword v234, v[236:237], off
	s_and_b64 vcc, exec, s[34:35]
	v_readfirstlane_b32 s24, v12
	s_cbranch_vccnz .LBB0_1226
	v_readlane_b32 s0, v232, 58
	s_mul_i32 s4, s0, 0x41
	s_lshl_b32 s5, s0, 6
	v_readlane_b32 s0, v232, 59
	v_readlane_b32 s1, v232, 60
	s_and_b64 s[0:1], s[0:1], exec
	s_cselect_b32 s0, s4, s5
	v_readlane_b32 s1, v232, 61
	s_add_i32 s0, s0, s1
	s_ashr_i32 s1, s0, 31
	s_lshr_b32 s1, s1, 27
	s_add_i32 s1, s0, s1
	s_ashr_i32 s4, s1, 5
	s_and_b32 s1, s1, 0xffe0
	s_sub_i32 s0, s0, s1
	s_bfe_i32 s1, s0, 0x80000
	s_bfe_u32 s1, s1, 0x2000d
	s_add_i32 s1, s0, s1
	s_bfe_i32 s5, s1, 0x80000
	s_and_b32 s1, s1, 0xfc
	s_sub_i32 s0, s0, s1
	s_lshl_b32 s4, s4, 2
	s_sext_i32_i16 s5, s5
	s_sext_i32_i8 s0, s0
	s_add_i32 s52, s4, s0
	s_ashr_i32 s14, s5, 2
